# adds: 256-byte alignment of attention tile loop, RG-LRU chunk loop and P0 loop heads
# speedup vs baseline: 1.0016x; 1.0016x over previous
.LBB0_10:
	s_add_i32 s28, s28, s10
	s_add_i32 s9, s9, s11
	s_add_i32 s18, s18, s19
	s_add_i32 s20, s20, s21
	s_cmp_gt_i32 s28, 0x160ff
	s_cbranch_scc1 .LBB0_45
	.p2align	8

.LBB0_45:
	s_cmpk_gt_i32 s8, 0x47ff
	v_mov_b32_e32 v67, 0
	s_cbranch_scc1 .LBB0_50
	v_mbcnt_lo_u32_b32 v1, -1, 0
	v_mbcnt_hi_u32_b32 v2, -1, v1
	v_and_b32_e32 v1, 64, v2
	v_add_u32_e32 v3, 64, v1
	v_xor_b32_e32 v1, 1, v2
	v_cmp_lt_i32_e32 vcc, v1, v3
	v_xor_b32_e32 v4, 2, v2
	v_lshlrev_b32_e32 v66, 3, v196
	v_cndmask_b32_e32 v1, v2, v1, vcc
	v_cmp_lt_i32_e32 vcc, v4, v3
	v_lshl_add_u64 v[68:69], s[86:87], 0, v[66:67]
	v_lshlrev_b32_e32 v66, 4, v196
	v_cndmask_b32_e32 v4, v2, v4, vcc
	v_lshlrev_b32_e32 v96, 2, v4
	v_xor_b32_e32 v4, 4, v2
	v_cmp_lt_i32_e32 vcc, v4, v3
	v_lshl_add_u64 v[70:71], s[64:65], 0, v[66:67]
	s_mov_b64 s[0:1], 0x1000
	v_cndmask_b32_e32 v4, v2, v4, vcc
	v_lshl_add_u64 v[72:73], v[70:71], 0, s[0:1]
	s_mov_b64 s[0:1], 0x1400
	v_lshlrev_b32_e32 v97, 2, v4
	v_xor_b32_e32 v4, 8, v2
	v_lshl_add_u64 v[74:75], v[70:71], 0, s[0:1]
	s_mov_b64 s[0:1], 0x1800
	v_cmp_lt_i32_e32 vcc, v4, v3
	v_lshl_add_u64 v[76:77], v[70:71], 0, s[0:1]
	s_mov_b64 s[0:1], 0x1c00
	v_cndmask_b32_e32 v4, v2, v4, vcc
	v_lshl_add_u64 v[78:79], v[70:71], 0, s[0:1]
	s_mov_b64 s[0:1], 0x2000
	v_lshlrev_b32_e32 v98, 2, v4
	v_xor_b32_e32 v4, 16, v2
	v_lshl_add_u64 v[80:81], v[70:71], 0, s[0:1]
	s_mov_b64 s[0:1], 0x2400
	v_cmp_lt_i32_e32 vcc, v4, v3
	v_lshl_add_u64 v[82:83], v[70:71], 0, s[0:1]
	s_mov_b64 s[0:1], 0x2800
	v_cndmask_b32_e32 v4, v2, v4, vcc
	v_lshl_add_u64 v[84:85], v[70:71], 0, s[0:1]
	s_mov_b64 s[0:1], 0x2c00
	v_lshlrev_b32_e32 v99, 2, v4
	v_xor_b32_e32 v4, 32, v2
	v_lshl_add_u64 v[86:87], v[70:71], 0, s[0:1]
	s_mov_b64 s[0:1], 0x3000
	v_cmp_lt_i32_e32 vcc, v4, v3
	v_lshl_add_u64 v[88:89], v[70:71], 0, s[0:1]
	s_mov_b64 s[0:1], 0x3400
	v_cndmask_b32_e32 v2, v2, v4, vcc
	v_lshl_add_u64 v[90:91], v[70:71], 0, s[0:1]
	s_mov_b64 s[0:1], 0x3800
	s_ashr_i32 s9, s8, 31
	v_lshlrev_b32_e32 v100, 2, v2
	v_lshl_add_u64 v[92:93], v[70:71], 0, s[0:1]
	v_mov_b32_e32 v2, 0x3c00
	s_ashr_i32 s11, s10, 31
	s_lshl_b64 s[0:1], s[8:9], 14
	v_lshl_or_b32 v2, v0, 4, v2
	v_mov_b32_e32 v3, v67
	s_add_u32 s12, s52, s0
	s_mov_b32 s5, 0
	v_lshlrev_b32_e32 v1, 2, v1
	v_lshl_add_u64 v[94:95], s[64:65], 0, v[2:3]
	s_addc_u32 s13, s53, s1
	s_lshl_b64 s[14:15], s[10:11], 14
	s_movk_i32 s20, 0x1000
	s_movk_i32 s21, 0x2000
	s_movk_i32 s28, 0x3000
	v_mov_b32_e32 v101, 0x358637bd
	s_mov_b32 s29, 0xf800000
	v_mov_b32_e32 v102, 0x260
	s_mov_b64 s[16:17], s[8:9]
	s_branch .LBB0_48
	.p2align	8

.LBB0_50:
	s_cmp_gt_i32 s8, 0xffff
	s_cbranch_scc1 .LBB0_53
	s_ashr_i32 s9, s8, 31
	s_lshl_b64 s[0:1], s[8:9], 12
	v_lshlrev_b32_e32 v4, 4, v196
	v_mov_b32_e32 v5, 0
	s_add_u32 s0, s56, s0
	v_lshl_add_u64 v[2:3], s[92:93], 0, v[4:5]
	v_lshlrev_b32_e32 v4, 5, v196
	s_addc_u32 s1, s57, s1
	v_lshl_add_u64 v[4:5], s[0:1], 0, v[4:5]
	s_mov_b64 s[0:1], 0x810
	s_ashr_i32 s11, s10, 31
	v_lshl_add_u64 v[4:5], v[4:5], 0, s[0:1]
	s_lshl_b64 s[0:1], s[10:11], 12
	s_mov_b32 s4, s8
	.p2align	8

.LBB0_328:
	s_or_b64 exec, exec, s[16:17]
	s_add_i32 s36, s36, s41
	s_cmpk_lt_i32 s36, 0x200
	s_cbranch_scc0 .LBB0_417
	.p2align	8

.LBB0_585:
	s_setprio 1
	.p2align	8
